# prologue: non-temporal hint on the bf16 weight-copy stores (on the full bundle with nt input loads)
# baseline (speedup 1.0000x reference)
.LBB0_8:
	s_waitcnt vmcnt(0)
	v_mul_f32_e32 v12, v33, v61
	v_mul_f32_e32 v13, v34, v60
	ds_write2_b32 v14, v12, v13 offset1:66
	v_mul_f32_e32 v12, v30, v63
	v_mul_f32_e32 v13, v31, v62
	ds_write2_b32 v14, v12, v13 offset0:132 offset1:198
	v_mul_f32_e32 v12, v28, v65
	v_mul_f32_e32 v13, v29, v64
	ds_write2_b32 v21, v12, v13 offset0:8 offset1:74
	v_mul_f32_e32 v9, v9, v67
	v_mul_f32_e32 v12, v32, v66
	ds_write2_b32 v21, v9, v12 offset0:140 offset1:206
	v_mul_f32_e32 v9, v41, v69
	v_mul_f32_e32 v12, v42, v68
	ds_write2_b32 v22, v9, v12 offset0:16 offset1:82
	v_mul_f32_e32 v9, v38, v71
	v_mul_f32_e32 v12, v39, v70
	ds_write2_b32 v22, v9, v12 offset0:148 offset1:214
	v_mul_f32_e32 v9, v36, v73
	v_mul_f32_e32 v12, v37, v72
	ds_write2_b32 v23, v9, v12 offset0:24 offset1:90
	v_mul_f32_e32 v9, v35, v75
	v_mul_f32_e32 v12, v40, v74
	ds_write2_b32 v23, v9, v12 offset0:156 offset1:222
	v_mul_f32_e32 v9, v49, v77
	v_mul_f32_e32 v12, v50, v76
	ds_write2_b32 v24, v9, v12 offset0:32 offset1:98
	v_mul_f32_e32 v9, v46, v79
	v_mul_f32_e32 v12, v47, v78
	ds_write2_b32 v24, v9, v12 offset0:164 offset1:230
	v_mul_f32_e32 v9, v44, v81
	v_mul_f32_e32 v12, v45, v80
	ds_write2_b32 v25, v9, v12 offset0:40 offset1:106
	v_mul_f32_e32 v9, v43, v83
	v_mul_f32_e32 v12, v48, v82
	ds_write2_b32 v25, v9, v12 offset0:172 offset1:238
	v_mul_f32_e32 v9, v58, v85
	v_mul_f32_e32 v12, v59, v84
	ds_write2_b32 v26, v9, v12 offset0:48 offset1:114
	v_mul_f32_e32 v9, v55, v87
	v_mul_f32_e32 v12, v57, v86
	ds_write2_b32 v26, v9, v12 offset0:180 offset1:246
	v_mul_f32_e32 v9, v52, v89
	v_mul_f32_e32 v12, v53, v88
	ds_write2_b32 v27, v9, v12 offset0:56 offset1:122
	v_mul_f32_e32 v9, v51, v91
	v_mul_f32_e32 v12, v54, v90
	ds_write2_b32 v27, v9, v12 offset0:188 offset1:254
	s_lshl_b32 s2, s2, 6
	s_waitcnt lgkmcnt(0)
	s_and_b32 s6, s54, 0x60
	s_and_b32 s2, s2, 0xffffff00
	ds_read2_b32 v[28:29], v16 offset0:33 offset1:41
	ds_read2_b32 v[30:31], v16 offset1:8
	ds_read2_b32 v[32:33], v16 offset0:66 offset1:74
	ds_read2_b32 v[34:35], v16 offset0:99 offset1:107
	ds_read2_b32 v[36:37], v16 offset0:132 offset1:140
	ds_read2_b32 v[38:39], v16 offset0:165 offset1:173
	ds_read2_b32 v[40:41], v16 offset0:198 offset1:206
	ds_read2_b32 v[42:43], v16 offset0:231 offset1:239
	s_or_b32 s2, s6, s2
	s_ashr_i32 s53, s52, 31
	v_or_b32_e32 v46, s2, v15
	v_lshl_add_u64 v[10:11], s[52:53], 1, v[10:11]
	v_mov_b32_e32 v9, v5
	v_ashrrev_i32_e32 v47, 31, v46
	v_lshl_add_u64 v[44:45], v[10:11], 0, v[8:9]
	v_lshlrev_b64 v[46:47], 11, v[46:47]
	s_waitcnt lgkmcnt(6)
	v_cvt_pk_bf16_f32 v10, v30, v28
	s_waitcnt lgkmcnt(4)
	v_cvt_pk_bf16_f32 v11, v32, v34
	s_waitcnt lgkmcnt(2)
	v_cvt_pk_bf16_f32 v12, v36, v38
	s_waitcnt lgkmcnt(0)
	v_cvt_pk_bf16_f32 v13, v40, v42
	v_lshl_add_u64 v[46:47], v[44:45], 0, v[46:47]
	v_or_b32_e32 v28, s2, v17
	global_store_dwordx4 v[46:47], v[10:13], off nt
	s_nop 1
	v_cvt_pk_bf16_f32 v10, v31, v29
	v_ashrrev_i32_e32 v29, 31, v28
	v_cvt_pk_bf16_f32 v11, v33, v35
	v_cvt_pk_bf16_f32 v12, v37, v39
	v_cvt_pk_bf16_f32 v13, v41, v43
	v_lshlrev_b64 v[28:29], 11, v[28:29]
	ds_read2_b32 v[30:31], v16 offset0:49 offset1:57
	ds_read2_b32 v[32:33], v16 offset0:16 offset1:24
	ds_read2_b32 v[34:35], v16 offset0:82 offset1:90
	ds_read2_b32 v[36:37], v16 offset0:115 offset1:123
	ds_read2_b32 v[38:39], v16 offset0:148 offset1:156
	ds_read2_b32 v[40:41], v16 offset0:181 offset1:189
	ds_read2_b32 v[42:43], v16 offset0:214 offset1:222
	ds_read2_b32 v[46:47], v16 offset0:247 offset1:255
	v_lshl_add_u64 v[28:29], v[44:45], 0, v[28:29]
	global_store_dwordx4 v[28:29], v[10:13], off nt
	v_or_b32_e32 v28, s2, v18
	v_ashrrev_i32_e32 v29, 31, v28
	v_lshlrev_b64 v[28:29], 11, v[28:29]
	s_waitcnt lgkmcnt(6)
	v_cvt_pk_bf16_f32 v10, v32, v30
	s_waitcnt lgkmcnt(4)
	v_cvt_pk_bf16_f32 v11, v34, v36
	s_waitcnt lgkmcnt(2)
	v_cvt_pk_bf16_f32 v12, v38, v40
	s_waitcnt lgkmcnt(0)
	v_cvt_pk_bf16_f32 v13, v42, v46
	v_lshl_add_u64 v[28:29], v[44:45], 0, v[28:29]
	global_store_dwordx4 v[28:29], v[10:13], off nt
	v_or_b32_e32 v28, s2, v19
	v_ashrrev_i32_e32 v29, 31, v28
	v_lshlrev_b64 v[28:29], 11, v[28:29]
	v_cvt_pk_bf16_f32 v10, v33, v31
	v_cvt_pk_bf16_f32 v11, v35, v37
	v_cvt_pk_bf16_f32 v12, v39, v41
	v_cvt_pk_bf16_f32 v13, v43, v47
	v_lshl_add_u64 v[28:29], v[44:45], 0, v[28:29]
	global_store_dwordx4 v[28:29], v[10:13], off nt
	s_waitcnt lgkmcnt(0)

.LBB0_10:
	s_mul_hi_i32 s2, s59, 0x67b23a55
	s_lshr_b32 s6, s2, 31
	s_ashr_i32 s2, s2, 12
	s_add_i32 s52, s2, s6
	s_mul_i32 s2, s52, 0xffffd880
	s_add_i32 s95, s59, s2
	s_ashr_i32 s53, s52, 31
	v_mad_i64_i32 v[10:11], s[6:7], s52, v20, v[6:7]
	s_cmpk_gt_i32 s95, 0x57f
	s_mov_b64 s[6:7], -1
	s_cbranch_scc0 .LBB0_292
	s_cmpk_gt_u32 s95, 0xaff
	s_cbranch_scc0 .LBB0_225
	s_cmpk_gt_u32 s95, 0x107f
	s_cbranch_scc0 .LBB0_222
	s_cmpk_gt_u32 s95, 0x15ff
	s_cbranch_scc0 .LBB0_155
	s_cmpk_gt_u32 s95, 0x1b7f
	s_cbranch_scc0 .LBB0_88
	s_cmpk_gt_u32 s95, 0x20ff
	s_cbranch_scc0 .LBB0_85
	s_cmpk_gt_u32 s95, 0x257f
	s_cbranch_scc0 .LBB0_18
	s_lshl_b64 s[6:7], s[52:53], 22
	s_add_u32 s54, s36, s6
	s_mul_i32 s2, s52, 0xffffb100
	s_addc_u32 s55, s37, s7
	s_add_i32 s2, s64, s2
	s_addk_i32 s2, 0xcb00
	s_and_b32 s6, s2, 0x1ffc0
	v_or_b32_e32 v9, s6, v3
	s_and_b32 s2, s62, 0x3e0
	v_lshlrev_b32_e32 v12, 12, v9
	v_mov_b32_e32 v13, v5
	v_lshl_add_u64 v[12:13], s[54:55], 0, v[12:13]
	s_lshl_b32 s46, s2, 2
	v_lshl_add_u64 v[12:13], v[12:13], 0, s[46:47]
	v_lshl_add_u64 v[12:13], v[12:13], 0, v[4:5]
	v_add_co_u32_e32 v28, vcc, s75, v12
	s_movk_i32 s7, 0x6000
	s_nop 0
	v_addc_co_u32_e32 v29, vcc, 0, v13, vcc
	v_add_co_u32_e32 v30, vcc, s67, v12
	s_lshl_b32 s46, s6, 1
	s_nop 0
	v_addc_co_u32_e32 v31, vcc, 0, v13, vcc
	v_add_co_u32_e32 v32, vcc, s7, v12
	s_mov_b32 s7, 0x8000
	s_nop 0
	v_addc_co_u32_e32 v33, vcc, 0, v13, vcc
	v_add_co_u32_e32 v34, vcc, s7, v12
	s_mov_b32 s7, 0xa000
	s_nop 0
	v_addc_co_u32_e32 v35, vcc, 0, v13, vcc
	v_add_co_u32_e32 v36, vcc, s7, v12
	s_mov_b32 s7, 0xc000
	s_nop 0
	v_addc_co_u32_e32 v37, vcc, 0, v13, vcc
	v_add_co_u32_e32 v38, vcc, s7, v12
	s_mov_b32 s7, 0xe000
	s_nop 0
	v_addc_co_u32_e32 v39, vcc, 0, v13, vcc
	v_add_co_u32_e32 v40, vcc, s7, v12
	s_mov_b32 s7, 0x14000
	s_nop 0
	v_addc_co_u32_e32 v41, vcc, 0, v13, vcc
	global_load_dword v9, v[12:13], off nt
	global_load_dword v44, v[28:29], off nt
	global_load_dword v45, v[30:31], off nt
	global_load_dword v46, v[32:33], off nt
	global_load_dword v47, v[34:35], off nt
	global_load_dword v48, v[36:37], off nt
	global_load_dword v49, v[38:39], off nt
	global_load_dword v50, v[40:41], off nt
	v_add_co_u32_e32 v28, vcc, s73, v12
	s_nop 1
	v_addc_co_u32_e32 v29, vcc, 0, v13, vcc
	v_add_co_u32_e32 v30, vcc, s76, v12
	s_nop 1
	v_addc_co_u32_e32 v31, vcc, 0, v13, vcc
	v_add_co_u32_e32 v32, vcc, s7, v12
	s_mov_b32 s7, 0x18000
	s_nop 0
	v_addc_co_u32_e32 v33, vcc, 0, v13, vcc
	v_add_co_u32_e32 v34, vcc, s78, v12
	s_nop 1
	v_addc_co_u32_e32 v35, vcc, 0, v13, vcc
	v_add_co_u32_e32 v36, vcc, s7, v12
	s_mov_b32 s7, 0x1a000
	s_nop 0
	v_addc_co_u32_e32 v37, vcc, 0, v13, vcc
	v_add_co_u32_e32 v38, vcc, s7, v12
	s_mov_b32 s7, 0x1c000
	s_nop 0
	v_addc_co_u32_e32 v39, vcc, 0, v13, vcc
	v_add_co_u32_e32 v40, vcc, s7, v12
	s_mov_b32 s7, 0x1e000
	s_nop 0
	v_addc_co_u32_e32 v41, vcc, 0, v13, vcc
	v_add_co_u32_e32 v42, vcc, s7, v12
	s_mov_b32 s7, 0x20000
	s_nop 0
	v_addc_co_u32_e32 v43, vcc, 0, v13, vcc
	global_load_dword v51, v[28:29], off nt
	global_load_dword v52, v[30:31], off nt
	global_load_dword v53, v[32:33], off nt
	global_load_dword v54, v[34:35], off nt
	global_load_dword v55, v[36:37], off nt
	global_load_dword v57, v[38:39], off nt
	global_load_dword v58, v[40:41], off nt
	global_load_dword v59, v[42:43], off nt
	v_add_co_u32_e32 v28, vcc, s7, v12
	s_mov_b32 s7, 0x22000
	s_nop 0
	v_addc_co_u32_e32 v29, vcc, 0, v13, vcc
	v_add_co_u32_e32 v30, vcc, s7, v12
	s_mov_b32 s7, 0x2a000
	s_nop 0
	v_addc_co_u32_e32 v31, vcc, 0, v13, vcc
	v_add_co_u32_e32 v32, vcc, s85, v12
	s_nop 1
	v_addc_co_u32_e32 v33, vcc, 0, v13, vcc
	v_add_co_u32_e32 v34, vcc, s86, v12
	s_nop 1
	v_addc_co_u32_e32 v35, vcc, 0, v13, vcc
	v_add_co_u32_e32 v36, vcc, s87, v12
	s_nop 1
	v_addc_co_u32_e32 v37, vcc, 0, v13, vcc
	v_add_co_u32_e32 v38, vcc, s7, v12
	s_mov_b32 s7, 0x2e000
	s_nop 0
	v_addc_co_u32_e32 v39, vcc, 0, v13, vcc
	v_add_co_u32_e32 v40, vcc, s89, v12
	s_nop 1
	v_addc_co_u32_e32 v41, vcc, 0, v13, vcc
	v_add_co_u32_e32 v42, vcc, s7, v12
	s_mov_b32 s7, 0x30000
	s_nop 0
	v_addc_co_u32_e32 v43, vcc, 0, v13, vcc
	global_load_dword v60, v[28:29], off nt
	global_load_dword v61, v[30:31], off nt
	global_load_dword v62, v[32:33], off nt
	global_load_dword v63, v[34:35], off nt
	global_load_dword v64, v[36:37], off nt
	global_load_dword v65, v[38:39], off nt
	global_load_dword v66, v[40:41], off nt
	s_nop 0
	global_load_dword v42, v[42:43], off nt
	v_add_co_u32_e32 v28, vcc, s7, v12
	s_mov_b32 s7, 0x32000
	s_nop 0
	v_addc_co_u32_e32 v29, vcc, 0, v13, vcc
	v_add_co_u32_e32 v30, vcc, s7, v12
	s_mov_b32 s7, 0x34000
	s_nop 0
	v_addc_co_u32_e32 v31, vcc, 0, v13, vcc
	v_add_co_u32_e32 v32, vcc, s7, v12
	s_mov_b32 s7, 0x38000
	s_nop 0
	v_addc_co_u32_e32 v33, vcc, 0, v13, vcc
	v_add_co_u32_e32 v34, vcc, s94, v12
	s_nop 1
	v_addc_co_u32_e32 v35, vcc, 0, v13, vcc
	v_add_co_u32_e32 v36, vcc, s7, v12
	s_mov_b64 s[6:7], 0x1500000
	s_nop 0
	v_addc_co_u32_e32 v37, vcc, 0, v13, vcc
	v_add_co_u32_e32 v38, vcc, s96, v12
	s_nop 1
	v_addc_co_u32_e32 v39, vcc, 0, v13, vcc
	v_add_co_u32_e32 v40, vcc, s97, v12
	s_nop 1
	v_addc_co_u32_e32 v41, vcc, 0, v13, vcc
	v_add_co_u32_e32 v12, vcc, s48, v12
	s_nop 1
	v_addc_co_u32_e32 v13, vcc, 0, v13, vcc
	global_load_dword v28, v[28:29], off nt
	s_nop 0
	global_load_dword v29, v[30:31], off nt
	s_nop 0
	global_load_dword v30, v[32:33], off nt
	global_load_dword v31, v[34:35], off nt
	s_nop 0
	global_load_dword v32, v[36:37], off nt
	global_load_dword v33, v[38:39], off nt
	global_load_dword v34, v[40:41], off nt
	s_nop 0
	global_load_dword v12, v[12:13], off nt
	s_waitcnt vmcnt(30)
	ds_write2_b32 v14, v9, v44 offset1:66
	s_waitcnt vmcnt(28)
	ds_write2_b32 v14, v45, v46 offset0:132 offset1:198
	s_waitcnt vmcnt(26)
	ds_write2_b32 v21, v47, v48 offset0:8 offset1:74
	s_waitcnt vmcnt(24)
	ds_write2_b32 v21, v49, v50 offset0:140 offset1:206
	s_waitcnt vmcnt(22)
	ds_write2_b32 v22, v51, v52 offset0:16 offset1:82
	s_waitcnt vmcnt(20)
	ds_write2_b32 v22, v53, v54 offset0:148 offset1:214
	s_waitcnt vmcnt(18)
	ds_write2_b32 v23, v55, v57 offset0:24 offset1:90
	s_waitcnt vmcnt(16)
	ds_write2_b32 v23, v58, v59 offset0:156 offset1:222
	s_waitcnt vmcnt(14)
	ds_write2_b32 v24, v60, v61 offset0:32 offset1:98
	s_waitcnt vmcnt(12)
	ds_write2_b32 v24, v62, v63 offset0:164 offset1:230
	s_waitcnt vmcnt(10)
	ds_write2_b32 v25, v64, v65 offset0:40 offset1:106
	s_waitcnt vmcnt(8)
	ds_write2_b32 v25, v66, v42 offset0:172 offset1:238
	s_waitcnt vmcnt(6)
	ds_write2_b32 v26, v28, v29 offset0:48 offset1:114
	s_waitcnt vmcnt(4)
	ds_write2_b32 v26, v30, v31 offset0:180 offset1:246
	s_waitcnt vmcnt(2)
	ds_write2_b32 v27, v32, v33 offset0:56 offset1:122
	s_waitcnt vmcnt(0)
	ds_write2_b32 v27, v34, v12 offset0:188 offset1:254
	s_waitcnt lgkmcnt(0)
	ds_read2_b32 v[32:33], v16 offset0:33 offset1:41
	ds_read2_b32 v[34:35], v16 offset1:8
	ds_read2_b32 v[36:37], v16 offset0:66 offset1:74
	ds_read2_b32 v[38:39], v16 offset0:99 offset1:107
	ds_read2_b32 v[40:41], v16 offset0:132 offset1:140
	ds_read2_b32 v[42:43], v16 offset0:165 offset1:173
	ds_read2_b32 v[44:45], v16 offset0:198 offset1:206
	ds_read2_b32 v[46:47], v16 offset0:231 offset1:239
	v_lshl_add_u64 v[12:13], v[10:11], 0, s[46:47]
	v_mov_b32_e32 v9, v5
	v_lshl_add_u64 v[12:13], v[12:13], 0, v[8:9]
	v_or_b32_e32 v9, s2, v15
	v_lshl_add_u64 v[12:13], v[12:13], 0, s[6:7]
	v_lshlrev_b32_e32 v48, 11, v9
	v_mov_b32_e32 v49, v5
	s_waitcnt lgkmcnt(6)
	v_cvt_pk_bf16_f32 v28, v34, v32
	s_waitcnt lgkmcnt(4)
	v_cvt_pk_bf16_f32 v29, v36, v38
	s_waitcnt lgkmcnt(2)
	v_cvt_pk_bf16_f32 v30, v40, v42
	s_waitcnt lgkmcnt(0)
	v_cvt_pk_bf16_f32 v31, v44, v46
	v_lshl_add_u64 v[48:49], v[12:13], 0, v[48:49]
	global_store_dwordx4 v[48:49], v[28:31], off nt
	v_or_b32_e32 v9, s2, v17
	v_lshlrev_b32_e32 v32, 11, v9
	v_cvt_pk_bf16_f32 v28, v35, v33
	v_cvt_pk_bf16_f32 v29, v37, v39
	v_cvt_pk_bf16_f32 v30, v41, v43
	v_cvt_pk_bf16_f32 v31, v45, v47
	ds_read2_b32 v[34:35], v16 offset0:49 offset1:57
	ds_read2_b32 v[36:37], v16 offset0:16 offset1:24
	ds_read2_b32 v[38:39], v16 offset0:82 offset1:90
	ds_read2_b32 v[40:41], v16 offset0:115 offset1:123
	ds_read2_b32 v[42:43], v16 offset0:148 offset1:156
	ds_read2_b32 v[44:45], v16 offset0:181 offset1:189
	ds_read2_b32 v[46:47], v16 offset0:214 offset1:222
	ds_read2_b32 v[48:49], v16 offset0:247 offset1:255
	v_mov_b32_e32 v33, v5
	v_lshl_add_u64 v[32:33], v[12:13], 0, v[32:33]
	v_or_b32_e32 v9, s2, v18
	global_store_dwordx4 v[32:33], v[28:31], off nt
	v_lshlrev_b32_e32 v32, 11, v9
	v_mov_b32_e32 v33, v5
	s_waitcnt lgkmcnt(6)
	v_cvt_pk_bf16_f32 v28, v36, v34
	s_waitcnt lgkmcnt(4)
	v_cvt_pk_bf16_f32 v29, v38, v40
	s_waitcnt lgkmcnt(2)
	v_cvt_pk_bf16_f32 v30, v42, v44
	s_waitcnt lgkmcnt(0)
	v_cvt_pk_bf16_f32 v31, v46, v48
	v_lshl_add_u64 v[32:33], v[12:13], 0, v[32:33]
	v_or_b32_e32 v9, s2, v19
	global_store_dwordx4 v[32:33], v[28:31], off nt
	v_lshlrev_b32_e32 v32, 11, v9
	v_mov_b32_e32 v33, v5
	v_cvt_pk_bf16_f32 v28, v37, v35
	v_cvt_pk_bf16_f32 v29, v39, v41
	v_cvt_pk_bf16_f32 v30, v43, v45
	v_cvt_pk_bf16_f32 v31, v47, v49
	v_lshl_add_u64 v[12:13], v[12:13], 0, v[32:33]
	global_store_dwordx4 v[12:13], v[28:31], off nt
	s_waitcnt lgkmcnt(0)
	s_mov_b64 s[6:7], 0

.LBB0_83:
	s_waitcnt vmcnt(0)
	v_mul_f32_e32 v12, v12, v64
	v_mul_f32_e32 v13, v13, v63
	ds_write2_b32 v21, v12, v13 offset0:8 offset1:74
	v_mul_f32_e32 v9, v9, v66
	v_mul_f32_e32 v12, v30, v65
	ds_write2_b32 v21, v9, v12 offset0:140 offset1:206
	v_mul_f32_e32 v9, v39, v68
	v_mul_f32_e32 v12, v40, v67
	ds_write2_b32 v22, v9, v12 offset0:16 offset1:82
	v_mul_f32_e32 v9, v36, v70
	v_mul_f32_e32 v12, v37, v69
	ds_write2_b32 v22, v9, v12 offset0:148 offset1:214
	v_mul_f32_e32 v9, v34, v72
	v_mul_f32_e32 v12, v35, v71
	ds_write2_b32 v23, v9, v12 offset0:24 offset1:90
	v_mul_f32_e32 v9, v33, v74
	v_mul_f32_e32 v12, v38, v73
	ds_write2_b32 v23, v9, v12 offset0:156 offset1:222
	v_mul_f32_e32 v9, v47, v76
	v_mul_f32_e32 v12, v48, v75
	ds_write2_b32 v24, v9, v12 offset0:32 offset1:98
	v_mul_f32_e32 v9, v44, v78
	v_mul_f32_e32 v12, v45, v77
	ds_write2_b32 v24, v9, v12 offset0:164 offset1:230
	v_mul_f32_e32 v9, v42, v80
	v_mul_f32_e32 v12, v43, v79
	ds_write2_b32 v25, v9, v12 offset0:40 offset1:106
	v_mul_f32_e32 v9, v41, v82
	v_mul_f32_e32 v12, v46, v81
	ds_write2_b32 v25, v9, v12 offset0:172 offset1:238
	v_mul_f32_e32 v9, v55, v84
	v_mul_f32_e32 v12, v57, v83
	ds_write2_b32 v26, v9, v12 offset0:48 offset1:114
	v_mul_f32_e32 v9, v53, v86
	v_mul_f32_e32 v12, v54, v85
	ds_write2_b32 v26, v9, v12 offset0:180 offset1:246
	v_mul_f32_e32 v9, v50, v88
	v_mul_f32_e32 v12, v51, v87
	v_mul_f32_e32 v31, v31, v59
	v_mul_f32_e32 v32, v32, v58
	v_mul_f32_e32 v28, v28, v62
	v_mul_f32_e32 v29, v29, v61
	ds_write2_b32 v27, v9, v12 offset0:56 offset1:122
	v_mul_f32_e32 v9, v49, v90
	v_mul_f32_e32 v12, v52, v89
	ds_write2_b32 v14, v31, v32 offset1:66
	ds_write2_b32 v14, v28, v29 offset0:132 offset1:198
	ds_write2_b32 v27, v9, v12 offset0:188 offset1:254
	s_waitcnt lgkmcnt(0)
	s_and_b32 s2, 0xffff, s2
	ds_read2_b32 v[32:33], v16 offset0:33 offset1:41
	ds_read2_b32 v[34:35], v16 offset1:8
	ds_read2_b32 v[36:37], v16 offset0:66 offset1:74
	ds_read2_b32 v[38:39], v16 offset0:99 offset1:107
	ds_read2_b32 v[40:41], v16 offset0:132 offset1:140
	ds_read2_b32 v[42:43], v16 offset0:165 offset1:173
	ds_read2_b32 v[44:45], v16 offset0:198 offset1:206
	ds_read2_b32 v[46:47], v16 offset0:231 offset1:239
	s_lshl_b32 s6, s56, 5
	s_lshl_b32 s46, s2, 1
	s_and_b32 s54, 0xffff, s6
	v_lshl_add_u64 v[12:13], v[10:11], 0, s[46:47]
	v_mov_b32_e32 v9, v5
	v_lshl_add_u64 v[12:13], v[12:13], 0, v[8:9]
	s_mov_b64 s[6:7], 0x1080000
	v_or_b32_e32 v9, s54, v15
	v_lshl_add_u64 v[12:13], v[12:13], 0, s[6:7]
	v_lshlrev_b32_e32 v48, 11, v9
	v_mov_b32_e32 v49, v5
	s_waitcnt lgkmcnt(6)
	v_cvt_pk_bf16_f32 v28, v34, v32
	s_waitcnt lgkmcnt(4)
	v_cvt_pk_bf16_f32 v29, v36, v38
	s_waitcnt lgkmcnt(2)
	v_cvt_pk_bf16_f32 v30, v40, v42
	s_waitcnt lgkmcnt(0)
	v_cvt_pk_bf16_f32 v31, v44, v46
	v_lshl_add_u64 v[48:49], v[12:13], 0, v[48:49]
	global_store_dwordx4 v[48:49], v[28:31], off nt
	v_or_b32_e32 v9, s54, v17
	v_lshlrev_b32_e32 v32, 11, v9
	v_cvt_pk_bf16_f32 v28, v35, v33
	v_cvt_pk_bf16_f32 v29, v37, v39
	v_cvt_pk_bf16_f32 v30, v41, v43
	v_cvt_pk_bf16_f32 v31, v45, v47
	ds_read2_b32 v[34:35], v16 offset0:49 offset1:57
	ds_read2_b32 v[36:37], v16 offset0:16 offset1:24
	ds_read2_b32 v[38:39], v16 offset0:82 offset1:90
	ds_read2_b32 v[40:41], v16 offset0:115 offset1:123
	ds_read2_b32 v[42:43], v16 offset0:148 offset1:156
	ds_read2_b32 v[44:45], v16 offset0:181 offset1:189
	ds_read2_b32 v[46:47], v16 offset0:214 offset1:222
	ds_read2_b32 v[48:49], v16 offset0:247 offset1:255
	v_mov_b32_e32 v33, v5
	v_lshl_add_u64 v[32:33], v[12:13], 0, v[32:33]
	v_or_b32_e32 v9, s54, v18
	global_store_dwordx4 v[32:33], v[28:31], off nt
	v_lshlrev_b32_e32 v32, 11, v9
	v_mov_b32_e32 v33, v5
	s_waitcnt lgkmcnt(6)
	v_cvt_pk_bf16_f32 v28, v36, v34
	s_waitcnt lgkmcnt(4)
	v_cvt_pk_bf16_f32 v29, v38, v40
	s_waitcnt lgkmcnt(2)
	v_cvt_pk_bf16_f32 v30, v42, v44
	s_waitcnt lgkmcnt(0)
	v_cvt_pk_bf16_f32 v31, v46, v48
	v_lshl_add_u64 v[32:33], v[12:13], 0, v[32:33]
	v_or_b32_e32 v9, s54, v19
	global_store_dwordx4 v[32:33], v[28:31], off nt
	v_lshlrev_b32_e32 v32, 11, v9
	v_mov_b32_e32 v33, v5
	v_cvt_pk_bf16_f32 v28, v37, v35
	v_cvt_pk_bf16_f32 v29, v39, v41
	v_cvt_pk_bf16_f32 v30, v43, v45
	v_cvt_pk_bf16_f32 v31, v47, v49
	v_lshl_add_u64 v[12:13], v[12:13], 0, v[32:33]
	global_store_dwordx4 v[12:13], v[28:31], off nt
	s_waitcnt lgkmcnt(0)

.LBB0_85:
	s_andn2_b64 vcc, exec, s[6:7]
	s_cbranch_vccnz .LBB0_87
	s_load_dwordx2 s[54:55], s[0:1], 0x90
	s_mul_i32 s6, s52, 0xb00000
	s_mul_hi_i32 s2, s52, 0xb00000
	v_mov_b32_e32 v13, v5
	s_movk_i32 s7, 0x6000
	s_waitcnt lgkmcnt(0)
	s_add_u32 s54, s54, s6
	s_addc_u32 s55, s55, s2
	s_mul_i32 s2, s52, 0xffffb100
	s_add_i32 s2, s64, s2
	s_addk_i32 s2, 0xdf00
	s_and_b32 s6, s2, 0x1ffc0
	v_or_b32_e32 v9, s6, v3
	s_and_b32 s2, s62, 0x3e0
	v_lshlrev_b32_e32 v12, 12, v9
	v_lshl_add_u64 v[12:13], s[54:55], 0, v[12:13]
	s_lshl_b32 s46, s2, 2
	v_lshl_add_u64 v[12:13], v[12:13], 0, s[46:47]
	v_lshl_add_u64 v[12:13], v[12:13], 0, v[4:5]
	v_add_co_u32_e32 v28, vcc, s75, v12
	s_lshl_b32 s46, s6, 1
	s_nop 0
	v_addc_co_u32_e32 v29, vcc, 0, v13, vcc
	v_add_co_u32_e32 v30, vcc, s67, v12
	s_nop 1
	v_addc_co_u32_e32 v31, vcc, 0, v13, vcc
	v_add_co_u32_e32 v32, vcc, s7, v12
	s_mov_b32 s7, 0x8000
	s_nop 0
	v_addc_co_u32_e32 v33, vcc, 0, v13, vcc
	v_add_co_u32_e32 v34, vcc, s7, v12
	s_mov_b32 s7, 0xa000
	s_nop 0
	v_addc_co_u32_e32 v35, vcc, 0, v13, vcc
	v_add_co_u32_e32 v36, vcc, s7, v12
	s_mov_b32 s7, 0xc000
	s_nop 0
	v_addc_co_u32_e32 v37, vcc, 0, v13, vcc
	v_add_co_u32_e32 v38, vcc, s7, v12
	s_mov_b32 s7, 0xe000
	s_nop 0
	v_addc_co_u32_e32 v39, vcc, 0, v13, vcc
	v_add_co_u32_e32 v40, vcc, s7, v12
	s_mov_b32 s7, 0x14000
	s_nop 0
	v_addc_co_u32_e32 v41, vcc, 0, v13, vcc
	global_load_dword v9, v[12:13], off nt
	global_load_dword v44, v[28:29], off nt
	global_load_dword v45, v[30:31], off nt
	global_load_dword v46, v[32:33], off nt
	global_load_dword v47, v[34:35], off nt
	global_load_dword v48, v[36:37], off nt
	global_load_dword v49, v[38:39], off nt
	global_load_dword v50, v[40:41], off nt
	v_add_co_u32_e32 v28, vcc, s73, v12
	s_nop 1
	v_addc_co_u32_e32 v29, vcc, 0, v13, vcc
	v_add_co_u32_e32 v30, vcc, s76, v12
	s_nop 1
	v_addc_co_u32_e32 v31, vcc, 0, v13, vcc
	v_add_co_u32_e32 v32, vcc, s7, v12
	s_mov_b32 s7, 0x18000
	s_nop 0
	v_addc_co_u32_e32 v33, vcc, 0, v13, vcc
	v_add_co_u32_e32 v34, vcc, s78, v12
	s_nop 1
	v_addc_co_u32_e32 v35, vcc, 0, v13, vcc
	v_add_co_u32_e32 v36, vcc, s7, v12
	s_mov_b32 s7, 0x1a000
	s_nop 0
	v_addc_co_u32_e32 v37, vcc, 0, v13, vcc
	v_add_co_u32_e32 v38, vcc, s7, v12
	s_mov_b32 s7, 0x1c000
	s_nop 0
	v_addc_co_u32_e32 v39, vcc, 0, v13, vcc
	v_add_co_u32_e32 v40, vcc, s7, v12
	s_mov_b32 s7, 0x1e000
	s_nop 0
	v_addc_co_u32_e32 v41, vcc, 0, v13, vcc
	v_add_co_u32_e32 v42, vcc, s7, v12
	s_mov_b32 s7, 0x20000
	s_nop 0
	v_addc_co_u32_e32 v43, vcc, 0, v13, vcc
	global_load_dword v51, v[28:29], off nt
	global_load_dword v52, v[30:31], off nt
	global_load_dword v53, v[32:33], off nt
	global_load_dword v54, v[34:35], off nt
	global_load_dword v55, v[36:37], off nt
	global_load_dword v57, v[38:39], off nt
	global_load_dword v58, v[40:41], off nt
	global_load_dword v59, v[42:43], off nt
	v_add_co_u32_e32 v28, vcc, s7, v12
	s_mov_b32 s7, 0x22000
	s_nop 0
	v_addc_co_u32_e32 v29, vcc, 0, v13, vcc
	v_add_co_u32_e32 v30, vcc, s7, v12
	s_mov_b32 s7, 0x2a000
	s_nop 0
	v_addc_co_u32_e32 v31, vcc, 0, v13, vcc
	v_add_co_u32_e32 v32, vcc, s85, v12
	s_nop 1
	v_addc_co_u32_e32 v33, vcc, 0, v13, vcc
	v_add_co_u32_e32 v34, vcc, s86, v12
	s_nop 1
	v_addc_co_u32_e32 v35, vcc, 0, v13, vcc
	v_add_co_u32_e32 v36, vcc, s87, v12
	s_nop 1
	v_addc_co_u32_e32 v37, vcc, 0, v13, vcc
	v_add_co_u32_e32 v38, vcc, s7, v12
	s_mov_b32 s7, 0x2e000
	s_nop 0
	v_addc_co_u32_e32 v39, vcc, 0, v13, vcc
	v_add_co_u32_e32 v40, vcc, s89, v12
	s_nop 1
	v_addc_co_u32_e32 v41, vcc, 0, v13, vcc
	v_add_co_u32_e32 v42, vcc, s7, v12
	s_mov_b32 s7, 0x30000
	s_nop 0
	v_addc_co_u32_e32 v43, vcc, 0, v13, vcc
	global_load_dword v60, v[28:29], off nt
	global_load_dword v61, v[30:31], off nt
	global_load_dword v62, v[32:33], off nt
	global_load_dword v63, v[34:35], off nt
	global_load_dword v64, v[36:37], off nt
	global_load_dword v65, v[38:39], off nt
	global_load_dword v66, v[40:41], off nt
	s_nop 0
	global_load_dword v42, v[42:43], off nt
	v_add_co_u32_e32 v28, vcc, s7, v12
	s_mov_b32 s7, 0x32000
	s_nop 0
	v_addc_co_u32_e32 v29, vcc, 0, v13, vcc
	v_add_co_u32_e32 v30, vcc, s7, v12
	s_mov_b32 s7, 0x34000
	s_nop 0
	v_addc_co_u32_e32 v31, vcc, 0, v13, vcc
	v_add_co_u32_e32 v32, vcc, s7, v12
	s_mov_b32 s7, 0x38000
	s_nop 0
	v_addc_co_u32_e32 v33, vcc, 0, v13, vcc
	v_add_co_u32_e32 v34, vcc, s94, v12
	s_nop 1
	v_addc_co_u32_e32 v35, vcc, 0, v13, vcc
	v_add_co_u32_e32 v36, vcc, s7, v12
	s_mov_b64 s[6:7], 0x2200000
	s_nop 0
	v_addc_co_u32_e32 v37, vcc, 0, v13, vcc
	v_add_co_u32_e32 v38, vcc, s96, v12
	s_nop 1
	v_addc_co_u32_e32 v39, vcc, 0, v13, vcc
	v_add_co_u32_e32 v40, vcc, s97, v12
	s_nop 1
	v_addc_co_u32_e32 v41, vcc, 0, v13, vcc
	v_add_co_u32_e32 v12, vcc, s48, v12
	s_nop 1
	v_addc_co_u32_e32 v13, vcc, 0, v13, vcc
	global_load_dword v28, v[28:29], off nt
	s_nop 0
	global_load_dword v29, v[30:31], off nt
	s_nop 0
	global_load_dword v30, v[32:33], off nt
	global_load_dword v31, v[34:35], off nt
	s_nop 0
	global_load_dword v32, v[36:37], off nt
	global_load_dword v33, v[38:39], off nt
	global_load_dword v34, v[40:41], off nt
	s_nop 0
	global_load_dword v12, v[12:13], off nt
	s_waitcnt vmcnt(30)
	ds_write2_b32 v14, v9, v44 offset1:66
	s_waitcnt vmcnt(28)
	ds_write2_b32 v14, v45, v46 offset0:132 offset1:198
	s_waitcnt vmcnt(26)
	ds_write2_b32 v21, v47, v48 offset0:8 offset1:74
	s_waitcnt vmcnt(24)
	ds_write2_b32 v21, v49, v50 offset0:140 offset1:206
	s_waitcnt vmcnt(22)
	ds_write2_b32 v22, v51, v52 offset0:16 offset1:82
	s_waitcnt vmcnt(20)
	ds_write2_b32 v22, v53, v54 offset0:148 offset1:214
	s_waitcnt vmcnt(18)
	ds_write2_b32 v23, v55, v57 offset0:24 offset1:90
	s_waitcnt vmcnt(16)
	ds_write2_b32 v23, v58, v59 offset0:156 offset1:222
	s_waitcnt vmcnt(14)
	ds_write2_b32 v24, v60, v61 offset0:32 offset1:98
	s_waitcnt vmcnt(12)
	ds_write2_b32 v24, v62, v63 offset0:164 offset1:230
	s_waitcnt vmcnt(10)
	ds_write2_b32 v25, v64, v65 offset0:40 offset1:106
	s_waitcnt vmcnt(8)
	ds_write2_b32 v25, v66, v42 offset0:172 offset1:238
	s_waitcnt vmcnt(6)
	ds_write2_b32 v26, v28, v29 offset0:48 offset1:114
	s_waitcnt vmcnt(4)
	ds_write2_b32 v26, v30, v31 offset0:180 offset1:246
	s_waitcnt vmcnt(2)
	ds_write2_b32 v27, v32, v33 offset0:56 offset1:122
	s_waitcnt vmcnt(0)
	ds_write2_b32 v27, v34, v12 offset0:188 offset1:254
	s_waitcnt lgkmcnt(0)
	ds_read2_b32 v[32:33], v16 offset0:33 offset1:41
	ds_read2_b32 v[34:35], v16 offset1:8
	ds_read2_b32 v[36:37], v16 offset0:66 offset1:74
	ds_read2_b32 v[38:39], v16 offset0:99 offset1:107
	ds_read2_b32 v[40:41], v16 offset0:132 offset1:140
	ds_read2_b32 v[42:43], v16 offset0:165 offset1:173
	ds_read2_b32 v[44:45], v16 offset0:198 offset1:206
	ds_read2_b32 v[46:47], v16 offset0:231 offset1:239
	v_lshl_add_u64 v[12:13], v[10:11], 0, s[46:47]
	v_mov_b32_e32 v9, v5
	v_lshl_add_u64 v[12:13], v[12:13], 0, v[8:9]
	v_or_b32_e32 v9, s2, v15
	v_mul_u32_u24_e32 v9, 0xb00, v9
	v_lshl_add_u64 v[12:13], v[12:13], 0, s[6:7]
	v_lshlrev_b32_e32 v48, 1, v9
	v_mov_b32_e32 v49, v5
	s_waitcnt lgkmcnt(6)
	v_cvt_pk_bf16_f32 v28, v34, v32
	s_waitcnt lgkmcnt(4)
	v_cvt_pk_bf16_f32 v29, v36, v38
	s_waitcnt lgkmcnt(2)
	v_cvt_pk_bf16_f32 v30, v40, v42
	s_waitcnt lgkmcnt(0)
	v_cvt_pk_bf16_f32 v31, v44, v46
	v_lshl_add_u64 v[48:49], v[12:13], 0, v[48:49]
	global_store_dwordx4 v[48:49], v[28:31], off nt
	v_or_b32_e32 v9, s2, v17
	v_mul_u32_u24_e32 v9, 0xb00, v9
	v_cvt_pk_bf16_f32 v28, v35, v33
	v_cvt_pk_bf16_f32 v29, v37, v39
	v_cvt_pk_bf16_f32 v30, v41, v43
	v_cvt_pk_bf16_f32 v31, v45, v47
	ds_read2_b32 v[34:35], v16 offset0:16 offset1:24
	ds_read2_b32 v[36:37], v16 offset0:49 offset1:57
	ds_read2_b32 v[38:39], v16 offset0:82 offset1:90
	ds_read2_b32 v[40:41], v16 offset0:115 offset1:123
	ds_read2_b32 v[42:43], v16 offset0:148 offset1:156
	ds_read2_b32 v[44:45], v16 offset0:181 offset1:189
	ds_read2_b32 v[46:47], v16 offset0:214 offset1:222
	ds_read2_b32 v[48:49], v16 offset0:247 offset1:255
	v_lshlrev_b32_e32 v32, 1, v9
	v_mov_b32_e32 v33, v5
	v_or_b32_e32 v9, s2, v18
	v_lshl_add_u64 v[32:33], v[12:13], 0, v[32:33]
	v_mul_u32_u24_e32 v9, 0xb00, v9
	global_store_dwordx4 v[32:33], v[28:31], off nt
	v_lshlrev_b32_e32 v32, 1, v9
	v_mov_b32_e32 v33, v5
	v_or_b32_e32 v9, s2, v19
	s_waitcnt lgkmcnt(6)
	v_cvt_pk_bf16_f32 v28, v34, v36
	s_waitcnt lgkmcnt(4)
	v_cvt_pk_bf16_f32 v29, v38, v40
	s_waitcnt lgkmcnt(2)
	v_cvt_pk_bf16_f32 v30, v42, v44
	s_waitcnt lgkmcnt(0)
	v_cvt_pk_bf16_f32 v31, v46, v48
	v_lshl_add_u64 v[32:33], v[12:13], 0, v[32:33]
	v_mul_u32_u24_e32 v9, 0xb00, v9
	global_store_dwordx4 v[32:33], v[28:31], off nt
	v_lshlrev_b32_e32 v32, 1, v9
	v_mov_b32_e32 v33, v5
	v_cvt_pk_bf16_f32 v28, v35, v37
	v_cvt_pk_bf16_f32 v29, v39, v41
	v_cvt_pk_bf16_f32 v30, v43, v45
	v_cvt_pk_bf16_f32 v31, v47, v49
	v_lshl_add_u64 v[12:13], v[12:13], 0, v[32:33]
	global_store_dwordx4 v[12:13], v[28:31], off nt
	s_waitcnt lgkmcnt(0)

.LBB0_153:
	s_waitcnt vmcnt(0)
	v_mul_f32_e32 v12, v12, v64
	v_mul_f32_e32 v13, v13, v63
	ds_write2_b32 v21, v12, v13 offset0:8 offset1:74
	v_mul_f32_e32 v9, v9, v66
	v_mul_f32_e32 v12, v30, v65
	ds_write2_b32 v21, v9, v12 offset0:140 offset1:206
	v_mul_f32_e32 v9, v39, v68
	v_mul_f32_e32 v12, v40, v67
	ds_write2_b32 v22, v9, v12 offset0:16 offset1:82
	v_mul_f32_e32 v9, v36, v70
	v_mul_f32_e32 v12, v37, v69
	ds_write2_b32 v22, v9, v12 offset0:148 offset1:214
	v_mul_f32_e32 v9, v34, v72
	v_mul_f32_e32 v12, v35, v71
	ds_write2_b32 v23, v9, v12 offset0:24 offset1:90
	v_mul_f32_e32 v9, v33, v74
	v_mul_f32_e32 v12, v38, v73
	ds_write2_b32 v23, v9, v12 offset0:156 offset1:222
	v_mul_f32_e32 v9, v47, v76
	v_mul_f32_e32 v12, v48, v75
	ds_write2_b32 v24, v9, v12 offset0:32 offset1:98
	v_mul_f32_e32 v9, v44, v78
	v_mul_f32_e32 v12, v45, v77
	ds_write2_b32 v24, v9, v12 offset0:164 offset1:230
	v_mul_f32_e32 v9, v42, v80
	v_mul_f32_e32 v12, v43, v79
	ds_write2_b32 v25, v9, v12 offset0:40 offset1:106
	v_mul_f32_e32 v9, v41, v82
	v_mul_f32_e32 v12, v46, v81
	ds_write2_b32 v25, v9, v12 offset0:172 offset1:238
	v_mul_f32_e32 v9, v55, v84
	v_mul_f32_e32 v12, v57, v83
	ds_write2_b32 v26, v9, v12 offset0:48 offset1:114
	v_mul_f32_e32 v9, v53, v86
	v_mul_f32_e32 v12, v54, v85
	ds_write2_b32 v26, v9, v12 offset0:180 offset1:246
	v_mul_f32_e32 v9, v50, v88
	v_mul_f32_e32 v12, v51, v87
	v_mul_f32_e32 v31, v31, v59
	v_mul_f32_e32 v32, v32, v58
	v_mul_f32_e32 v28, v28, v62
	v_mul_f32_e32 v29, v29, v61
	ds_write2_b32 v27, v9, v12 offset0:56 offset1:122
	v_mul_f32_e32 v9, v49, v90
	v_mul_f32_e32 v12, v52, v89
	ds_write2_b32 v14, v31, v32 offset1:66
	ds_write2_b32 v14, v28, v29 offset0:132 offset1:198
	ds_write2_b32 v27, v9, v12 offset0:188 offset1:254
	s_lshl_b32 s6, s56, 5
	s_lshl_b32 s7, s56, 6
	s_waitcnt lgkmcnt(0)
	s_and_b32 s6, s6, 0x60
	s_and_b32 s7, s7, 0x1f00
	s_and_b32 s2, 0xffff, s2
	ds_read2_b32 v[32:33], v16 offset0:33 offset1:41
	ds_read2_b32 v[34:35], v16 offset1:8
	ds_read2_b32 v[36:37], v16 offset0:66 offset1:74
	ds_read2_b32 v[38:39], v16 offset0:99 offset1:107
	ds_read2_b32 v[40:41], v16 offset0:132 offset1:140
	ds_read2_b32 v[42:43], v16 offset0:165 offset1:173
	ds_read2_b32 v[44:45], v16 offset0:198 offset1:206
	ds_read2_b32 v[46:47], v16 offset0:231 offset1:239
	s_or_b32 s6, s6, s7
	s_lshl_b32 s46, s2, 1
	s_bitset1_b32 s6, 7
	v_lshl_add_u64 v[12:13], v[10:11], 0, s[46:47]
	v_mov_b32_e32 v9, v5
	v_lshl_add_u64 v[12:13], v[12:13], 0, v[8:9]
	s_mov_b64 s[54:55], 0x1700000
	v_or_b32_e32 v9, s6, v15
	v_lshl_add_u64 v[12:13], v[12:13], 0, s[54:55]
	v_lshlrev_b32_e32 v48, 11, v9
	v_mov_b32_e32 v49, v5
	s_waitcnt lgkmcnt(6)
	v_cvt_pk_bf16_f32 v28, v34, v32
	s_waitcnt lgkmcnt(4)
	v_cvt_pk_bf16_f32 v29, v36, v38
	s_waitcnt lgkmcnt(2)
	v_cvt_pk_bf16_f32 v30, v40, v42
	s_waitcnt lgkmcnt(0)
	v_cvt_pk_bf16_f32 v31, v44, v46
	v_lshl_add_u64 v[48:49], v[12:13], 0, v[48:49]
	global_store_dwordx4 v[48:49], v[28:31], off nt
	v_or_b32_e32 v9, s6, v17
	v_lshlrev_b32_e32 v32, 11, v9
	v_cvt_pk_bf16_f32 v28, v35, v33
	v_cvt_pk_bf16_f32 v29, v37, v39
	v_cvt_pk_bf16_f32 v30, v41, v43
	v_cvt_pk_bf16_f32 v31, v45, v47
	ds_read2_b32 v[34:35], v16 offset0:49 offset1:57
	ds_read2_b32 v[36:37], v16 offset0:16 offset1:24
	ds_read2_b32 v[38:39], v16 offset0:82 offset1:90
	ds_read2_b32 v[40:41], v16 offset0:115 offset1:123
	ds_read2_b32 v[42:43], v16 offset0:148 offset1:156
	ds_read2_b32 v[44:45], v16 offset0:181 offset1:189
	ds_read2_b32 v[46:47], v16 offset0:214 offset1:222
	ds_read2_b32 v[48:49], v16 offset0:247 offset1:255
	v_mov_b32_e32 v33, v5
	v_lshl_add_u64 v[32:33], v[12:13], 0, v[32:33]
	v_or_b32_e32 v9, s6, v18
	global_store_dwordx4 v[32:33], v[28:31], off nt
	v_lshlrev_b32_e32 v32, 11, v9
	v_mov_b32_e32 v33, v5
	s_waitcnt lgkmcnt(6)
	v_cvt_pk_bf16_f32 v28, v36, v34
	s_waitcnt lgkmcnt(4)
	v_cvt_pk_bf16_f32 v29, v38, v40
	s_waitcnt lgkmcnt(2)
	v_cvt_pk_bf16_f32 v30, v42, v44
	s_waitcnt lgkmcnt(0)
	v_cvt_pk_bf16_f32 v31, v46, v48
	v_lshl_add_u64 v[32:33], v[12:13], 0, v[32:33]
	v_or_b32_e32 v9, s6, v19
	global_store_dwordx4 v[32:33], v[28:31], off nt
	v_lshlrev_b32_e32 v32, 11, v9
	v_mov_b32_e32 v33, v5
	v_cvt_pk_bf16_f32 v28, v37, v35
	v_cvt_pk_bf16_f32 v29, v39, v41
	v_cvt_pk_bf16_f32 v30, v43, v45
	v_cvt_pk_bf16_f32 v31, v47, v49
	v_lshl_add_u64 v[12:13], v[12:13], 0, v[32:33]
	global_store_dwordx4 v[12:13], v[28:31], off nt
	s_waitcnt lgkmcnt(0)

.LBB0_220:
	s_waitcnt vmcnt(0)
	v_mul_f32_e32 v12, v12, v64
	v_mul_f32_e32 v13, v13, v63
	ds_write2_b32 v21, v12, v13 offset0:8 offset1:74
	v_mul_f32_e32 v9, v9, v66
	v_mul_f32_e32 v12, v30, v65
	ds_write2_b32 v21, v9, v12 offset0:140 offset1:206
	v_mul_f32_e32 v9, v39, v68
	v_mul_f32_e32 v12, v40, v67
	ds_write2_b32 v22, v9, v12 offset0:16 offset1:82
	v_mul_f32_e32 v9, v36, v70
	v_mul_f32_e32 v12, v37, v69
	ds_write2_b32 v22, v9, v12 offset0:148 offset1:214
	v_mul_f32_e32 v9, v34, v72
	v_mul_f32_e32 v12, v35, v71
	ds_write2_b32 v23, v9, v12 offset0:24 offset1:90
	v_mul_f32_e32 v9, v33, v74
	v_mul_f32_e32 v12, v38, v73
	ds_write2_b32 v23, v9, v12 offset0:156 offset1:222
	v_mul_f32_e32 v9, v47, v76
	v_mul_f32_e32 v12, v48, v75
	ds_write2_b32 v24, v9, v12 offset0:32 offset1:98
	v_mul_f32_e32 v9, v44, v78
	v_mul_f32_e32 v12, v45, v77
	ds_write2_b32 v24, v9, v12 offset0:164 offset1:230
	v_mul_f32_e32 v9, v42, v80
	v_mul_f32_e32 v12, v43, v79
	ds_write2_b32 v25, v9, v12 offset0:40 offset1:106
	v_mul_f32_e32 v9, v41, v82
	v_mul_f32_e32 v12, v46, v81
	ds_write2_b32 v25, v9, v12 offset0:172 offset1:238
	v_mul_f32_e32 v9, v55, v84
	v_mul_f32_e32 v12, v57, v83
	ds_write2_b32 v26, v9, v12 offset0:48 offset1:114
	v_mul_f32_e32 v9, v53, v86
	v_mul_f32_e32 v12, v54, v85
	ds_write2_b32 v26, v9, v12 offset0:180 offset1:246
	v_mul_f32_e32 v9, v50, v88
	v_mul_f32_e32 v12, v51, v87
	v_mul_f32_e32 v31, v31, v59
	v_mul_f32_e32 v32, v32, v58
	v_mul_f32_e32 v28, v28, v62
	v_mul_f32_e32 v29, v29, v61
	ds_write2_b32 v27, v9, v12 offset0:56 offset1:122
	v_mul_f32_e32 v9, v49, v90
	v_mul_f32_e32 v12, v52, v89
	ds_write2_b32 v14, v31, v32 offset1:66
	ds_write2_b32 v14, v28, v29 offset0:132 offset1:198
	ds_write2_b32 v27, v9, v12 offset0:188 offset1:254
	s_waitcnt lgkmcnt(0)
	s_lshl_b32 s6, s56, 5
	s_lshl_b32 s7, s56, 6
	s_and_b32 s2, 0xffff, s2
	ds_read2_b32 v[32:33], v16 offset0:33 offset1:41
	ds_read2_b32 v[34:35], v16 offset1:8
	ds_read2_b32 v[36:37], v16 offset0:66 offset1:74
	ds_read2_b32 v[38:39], v16 offset0:99 offset1:107
	ds_read2_b32 v[40:41], v16 offset0:132 offset1:140
	ds_read2_b32 v[42:43], v16 offset0:165 offset1:173
	ds_read2_b32 v[44:45], v16 offset0:198 offset1:206
	ds_read2_b32 v[46:47], v16 offset0:231 offset1:239
	s_and_b32 s6, s6, 0x60
	s_and_b32 s7, s7, 0x1f00
	s_lshl_b32 s46, s2, 1
	s_or_b32 s6, s6, s7
	v_lshl_add_u64 v[12:13], v[10:11], 0, s[46:47]
	v_mov_b32_e32 v9, v5
	v_lshl_add_u64 v[12:13], v[12:13], 0, v[8:9]
	s_mov_b64 s[54:55], 0x1700000
	v_or_b32_e32 v9, s6, v15
	v_lshl_add_u64 v[12:13], v[12:13], 0, s[54:55]
	v_lshlrev_b32_e32 v48, 11, v9
	v_mov_b32_e32 v49, v5
	s_waitcnt lgkmcnt(6)
	v_cvt_pk_bf16_f32 v28, v34, v32
	s_waitcnt lgkmcnt(4)
	v_cvt_pk_bf16_f32 v29, v36, v38
	s_waitcnt lgkmcnt(2)
	v_cvt_pk_bf16_f32 v30, v40, v42
	s_waitcnt lgkmcnt(0)
	v_cvt_pk_bf16_f32 v31, v44, v46
	v_lshl_add_u64 v[48:49], v[12:13], 0, v[48:49]
	global_store_dwordx4 v[48:49], v[28:31], off nt
	v_or_b32_e32 v9, s6, v17
	v_lshlrev_b32_e32 v32, 11, v9
	v_cvt_pk_bf16_f32 v28, v35, v33
	v_cvt_pk_bf16_f32 v29, v37, v39
	v_cvt_pk_bf16_f32 v30, v41, v43
	v_cvt_pk_bf16_f32 v31, v45, v47
	ds_read2_b32 v[34:35], v16 offset0:49 offset1:57
	ds_read2_b32 v[36:37], v16 offset0:16 offset1:24
	ds_read2_b32 v[38:39], v16 offset0:82 offset1:90
	ds_read2_b32 v[40:41], v16 offset0:115 offset1:123
	ds_read2_b32 v[42:43], v16 offset0:148 offset1:156
	ds_read2_b32 v[44:45], v16 offset0:181 offset1:189
	ds_read2_b32 v[46:47], v16 offset0:214 offset1:222
	ds_read2_b32 v[48:49], v16 offset0:247 offset1:255
	v_mov_b32_e32 v33, v5
	v_lshl_add_u64 v[32:33], v[12:13], 0, v[32:33]
	v_or_b32_e32 v9, s6, v18
	global_store_dwordx4 v[32:33], v[28:31], off nt
	v_lshlrev_b32_e32 v32, 11, v9
	v_mov_b32_e32 v33, v5
	s_waitcnt lgkmcnt(6)
	v_cvt_pk_bf16_f32 v28, v36, v34
	s_waitcnt lgkmcnt(4)
	v_cvt_pk_bf16_f32 v29, v38, v40
	s_waitcnt lgkmcnt(2)
	v_cvt_pk_bf16_f32 v30, v42, v44
	s_waitcnt lgkmcnt(0)
	v_cvt_pk_bf16_f32 v31, v46, v48
	v_lshl_add_u64 v[32:33], v[12:13], 0, v[32:33]
	v_or_b32_e32 v9, s6, v19
	global_store_dwordx4 v[32:33], v[28:31], off nt
	v_lshlrev_b32_e32 v32, 11, v9
	v_mov_b32_e32 v33, v5
	v_cvt_pk_bf16_f32 v28, v37, v35
	v_cvt_pk_bf16_f32 v29, v39, v41
	v_cvt_pk_bf16_f32 v30, v43, v45
	v_cvt_pk_bf16_f32 v31, v47, v49
	v_lshl_add_u64 v[12:13], v[12:13], 0, v[32:33]
	global_store_dwordx4 v[12:13], v[28:31], off nt
	s_waitcnt lgkmcnt(0)

.LBB0_222:
	s_andn2_b64 vcc, exec, s[6:7]
	s_cbranch_vccnz .LBB0_224
	s_mul_i32 s6, s52, 0xb00000
	s_mul_hi_i32 s2, s52, 0xb00000
	s_add_u32 s54, s26, s6
	s_addc_u32 s55, s27, s2
	s_mul_i32 s2, s52, 0xffffb100
	s_add_i32 s2, s64, s2
	s_and_b32 s6, s2, 0x1ffc0
	v_or_b32_e32 v9, s6, v3
	s_and_b32 s2, s62, 0x3e0
	v_lshlrev_b32_e32 v12, 12, v9
	v_mov_b32_e32 v13, v5
	v_lshl_add_u64 v[12:13], s[54:55], 0, v[12:13]
	s_lshl_b32 s46, s2, 2
	v_lshl_add_u64 v[12:13], v[12:13], 0, s[46:47]
	v_lshl_add_u64 v[12:13], v[12:13], 0, v[4:5]
	v_add_co_u32_e32 v28, vcc, s75, v12
	s_movk_i32 s7, 0x6000
	s_nop 0
	v_addc_co_u32_e32 v29, vcc, 0, v13, vcc
	v_add_co_u32_e32 v30, vcc, s67, v12
	s_lshl_b32 s46, s6, 1
	s_nop 0
	v_addc_co_u32_e32 v31, vcc, 0, v13, vcc
	v_add_co_u32_e32 v32, vcc, s7, v12
	s_mov_b32 s7, 0x8000
	s_nop 0
	v_addc_co_u32_e32 v33, vcc, 0, v13, vcc
	v_add_co_u32_e32 v34, vcc, s7, v12
	s_mov_b32 s7, 0xa000
	s_nop 0
	v_addc_co_u32_e32 v35, vcc, 0, v13, vcc
	v_add_co_u32_e32 v36, vcc, s7, v12
	s_mov_b32 s7, 0xc000
	s_nop 0
	v_addc_co_u32_e32 v37, vcc, 0, v13, vcc
	v_add_co_u32_e32 v38, vcc, s7, v12
	s_mov_b32 s7, 0xe000
	s_nop 0
	v_addc_co_u32_e32 v39, vcc, 0, v13, vcc
	v_add_co_u32_e32 v40, vcc, s7, v12
	s_mov_b32 s7, 0x14000
	s_nop 0
	v_addc_co_u32_e32 v41, vcc, 0, v13, vcc
	global_load_dword v9, v[12:13], off nt
	global_load_dword v44, v[28:29], off nt
	global_load_dword v45, v[30:31], off nt
	global_load_dword v46, v[32:33], off nt
	global_load_dword v47, v[34:35], off nt
	global_load_dword v48, v[36:37], off nt
	global_load_dword v49, v[38:39], off nt
	global_load_dword v50, v[40:41], off nt
	v_add_co_u32_e32 v28, vcc, s73, v12
	s_nop 1
	v_addc_co_u32_e32 v29, vcc, 0, v13, vcc
	v_add_co_u32_e32 v30, vcc, s76, v12
	s_nop 1
	v_addc_co_u32_e32 v31, vcc, 0, v13, vcc
	v_add_co_u32_e32 v32, vcc, s7, v12
	s_mov_b32 s7, 0x18000
	s_nop 0
	v_addc_co_u32_e32 v33, vcc, 0, v13, vcc
	v_add_co_u32_e32 v34, vcc, s78, v12
	s_nop 1
	v_addc_co_u32_e32 v35, vcc, 0, v13, vcc
	v_add_co_u32_e32 v36, vcc, s7, v12
	s_mov_b32 s7, 0x1a000
	s_nop 0
	v_addc_co_u32_e32 v37, vcc, 0, v13, vcc
	v_add_co_u32_e32 v38, vcc, s7, v12
	s_mov_b32 s7, 0x1c000
	s_nop 0
	v_addc_co_u32_e32 v39, vcc, 0, v13, vcc
	v_add_co_u32_e32 v40, vcc, s7, v12
	s_mov_b32 s7, 0x1e000
	s_nop 0
	v_addc_co_u32_e32 v41, vcc, 0, v13, vcc
	v_add_co_u32_e32 v42, vcc, s7, v12
	s_mov_b32 s7, 0x20000
	s_nop 0
	v_addc_co_u32_e32 v43, vcc, 0, v13, vcc
	global_load_dword v51, v[28:29], off nt
	global_load_dword v52, v[30:31], off nt
	global_load_dword v53, v[32:33], off nt
	global_load_dword v54, v[34:35], off nt
	global_load_dword v55, v[36:37], off nt
	global_load_dword v57, v[38:39], off nt
	global_load_dword v58, v[40:41], off nt
	global_load_dword v59, v[42:43], off nt
	v_add_co_u32_e32 v28, vcc, s7, v12
	s_mov_b32 s7, 0x22000
	s_nop 0
	v_addc_co_u32_e32 v29, vcc, 0, v13, vcc
	v_add_co_u32_e32 v30, vcc, s7, v12
	s_mov_b32 s7, 0x2a000
	s_nop 0
	v_addc_co_u32_e32 v31, vcc, 0, v13, vcc
	v_add_co_u32_e32 v32, vcc, s85, v12
	s_nop 1
	v_addc_co_u32_e32 v33, vcc, 0, v13, vcc
	v_add_co_u32_e32 v34, vcc, s86, v12
	s_nop 1
	v_addc_co_u32_e32 v35, vcc, 0, v13, vcc
	v_add_co_u32_e32 v36, vcc, s87, v12
	s_nop 1
	v_addc_co_u32_e32 v37, vcc, 0, v13, vcc
	v_add_co_u32_e32 v38, vcc, s7, v12
	s_mov_b32 s7, 0x2e000
	s_nop 0
	v_addc_co_u32_e32 v39, vcc, 0, v13, vcc
	v_add_co_u32_e32 v40, vcc, s89, v12
	s_nop 1
	v_addc_co_u32_e32 v41, vcc, 0, v13, vcc
	v_add_co_u32_e32 v42, vcc, s7, v12
	s_mov_b32 s7, 0x30000
	s_nop 0
	v_addc_co_u32_e32 v43, vcc, 0, v13, vcc
	global_load_dword v60, v[28:29], off nt
	global_load_dword v61, v[30:31], off nt
	global_load_dword v62, v[32:33], off nt
	global_load_dword v63, v[34:35], off nt
	global_load_dword v64, v[36:37], off nt
	global_load_dword v65, v[38:39], off nt
	global_load_dword v66, v[40:41], off nt
	s_nop 0
	global_load_dword v42, v[42:43], off nt
	v_add_co_u32_e32 v28, vcc, s7, v12
	s_mov_b32 s7, 0x32000
	s_nop 0
	v_addc_co_u32_e32 v29, vcc, 0, v13, vcc
	v_add_co_u32_e32 v30, vcc, s7, v12
	s_mov_b32 s7, 0x34000
	s_nop 0
	v_addc_co_u32_e32 v31, vcc, 0, v13, vcc
	v_add_co_u32_e32 v32, vcc, s7, v12
	s_mov_b32 s7, 0x38000
	s_nop 0
	v_addc_co_u32_e32 v33, vcc, 0, v13, vcc
	v_add_co_u32_e32 v34, vcc, s94, v12
	s_nop 1
	v_addc_co_u32_e32 v35, vcc, 0, v13, vcc
	v_add_co_u32_e32 v36, vcc, s7, v12
	s_mov_b64 s[6:7], 0xb00000
	s_nop 0
	v_addc_co_u32_e32 v37, vcc, 0, v13, vcc
	v_add_co_u32_e32 v38, vcc, s96, v12
	s_nop 1
	v_addc_co_u32_e32 v39, vcc, 0, v13, vcc
	v_add_co_u32_e32 v40, vcc, s97, v12
	s_nop 1
	v_addc_co_u32_e32 v41, vcc, 0, v13, vcc
	v_add_co_u32_e32 v12, vcc, s48, v12
	s_nop 1
	v_addc_co_u32_e32 v13, vcc, 0, v13, vcc
	global_load_dword v28, v[28:29], off nt
	s_nop 0
	global_load_dword v29, v[30:31], off nt
	s_nop 0
	global_load_dword v30, v[32:33], off nt
	global_load_dword v31, v[34:35], off nt
	s_nop 0
	global_load_dword v32, v[36:37], off nt
	global_load_dword v33, v[38:39], off nt
	global_load_dword v34, v[40:41], off nt
	s_nop 0
	global_load_dword v12, v[12:13], off nt
	s_waitcnt vmcnt(30)
	ds_write2_b32 v14, v9, v44 offset1:66
	s_waitcnt vmcnt(28)
	ds_write2_b32 v14, v45, v46 offset0:132 offset1:198
	s_waitcnt vmcnt(26)
	ds_write2_b32 v21, v47, v48 offset0:8 offset1:74
	s_waitcnt vmcnt(24)
	ds_write2_b32 v21, v49, v50 offset0:140 offset1:206
	s_waitcnt vmcnt(22)
	ds_write2_b32 v22, v51, v52 offset0:16 offset1:82
	s_waitcnt vmcnt(20)
	ds_write2_b32 v22, v53, v54 offset0:148 offset1:214
	s_waitcnt vmcnt(18)
	ds_write2_b32 v23, v55, v57 offset0:24 offset1:90
	s_waitcnt vmcnt(16)
	ds_write2_b32 v23, v58, v59 offset0:156 offset1:222
	s_waitcnt vmcnt(14)
	ds_write2_b32 v24, v60, v61 offset0:32 offset1:98
	s_waitcnt vmcnt(12)
	ds_write2_b32 v24, v62, v63 offset0:164 offset1:230
	s_waitcnt vmcnt(10)
	ds_write2_b32 v25, v64, v65 offset0:40 offset1:106
	s_waitcnt vmcnt(8)
	ds_write2_b32 v25, v66, v42 offset0:172 offset1:238
	s_waitcnt vmcnt(6)
	ds_write2_b32 v26, v28, v29 offset0:48 offset1:114
	s_waitcnt vmcnt(4)
	ds_write2_b32 v26, v30, v31 offset0:180 offset1:246
	s_waitcnt vmcnt(2)
	ds_write2_b32 v27, v32, v33 offset0:56 offset1:122
	s_waitcnt vmcnt(0)
	ds_write2_b32 v27, v34, v12 offset0:188 offset1:254
	s_waitcnt lgkmcnt(0)
	ds_read2_b32 v[32:33], v16 offset0:33 offset1:41
	ds_read2_b32 v[34:35], v16 offset1:8
	ds_read2_b32 v[36:37], v16 offset0:66 offset1:74
	ds_read2_b32 v[38:39], v16 offset0:99 offset1:107
	ds_read2_b32 v[40:41], v16 offset0:132 offset1:140
	ds_read2_b32 v[42:43], v16 offset0:165 offset1:173
	ds_read2_b32 v[44:45], v16 offset0:198 offset1:206
	ds_read2_b32 v[46:47], v16 offset0:231 offset1:239
	v_lshl_add_u64 v[12:13], v[10:11], 0, s[46:47]
	v_mov_b32_e32 v9, v5
	v_lshl_add_u64 v[12:13], v[12:13], 0, v[8:9]
	v_or_b32_e32 v9, s2, v15
	v_mul_u32_u24_e32 v9, 0xb00, v9
	v_lshl_add_u64 v[12:13], v[12:13], 0, s[6:7]
	v_lshlrev_b32_e32 v48, 1, v9
	v_mov_b32_e32 v49, v5
	s_waitcnt lgkmcnt(6)
	v_cvt_pk_bf16_f32 v28, v34, v32
	s_waitcnt lgkmcnt(4)
	v_cvt_pk_bf16_f32 v29, v36, v38
	s_waitcnt lgkmcnt(2)
	v_cvt_pk_bf16_f32 v30, v40, v42
	s_waitcnt lgkmcnt(0)
	v_cvt_pk_bf16_f32 v31, v44, v46
	v_lshl_add_u64 v[48:49], v[12:13], 0, v[48:49]
	global_store_dwordx4 v[48:49], v[28:31], off nt
	v_or_b32_e32 v9, s2, v17
	v_mul_u32_u24_e32 v9, 0xb00, v9
	v_cvt_pk_bf16_f32 v28, v35, v33
	v_cvt_pk_bf16_f32 v29, v37, v39
	v_cvt_pk_bf16_f32 v30, v41, v43
	v_cvt_pk_bf16_f32 v31, v45, v47
	ds_read2_b32 v[34:35], v16 offset0:16 offset1:24
	ds_read2_b32 v[36:37], v16 offset0:49 offset1:57
	ds_read2_b32 v[38:39], v16 offset0:82 offset1:90
	ds_read2_b32 v[40:41], v16 offset0:115 offset1:123
	ds_read2_b32 v[42:43], v16 offset0:148 offset1:156
	ds_read2_b32 v[44:45], v16 offset0:181 offset1:189
	ds_read2_b32 v[46:47], v16 offset0:214 offset1:222
	ds_read2_b32 v[48:49], v16 offset0:247 offset1:255
	v_lshlrev_b32_e32 v32, 1, v9
	v_mov_b32_e32 v33, v5
	v_or_b32_e32 v9, s2, v18
	v_lshl_add_u64 v[32:33], v[12:13], 0, v[32:33]
	v_mul_u32_u24_e32 v9, 0xb00, v9
	global_store_dwordx4 v[32:33], v[28:31], off nt
	v_lshlrev_b32_e32 v32, 1, v9
	v_mov_b32_e32 v33, v5
	v_or_b32_e32 v9, s2, v19
	s_waitcnt lgkmcnt(6)
	v_cvt_pk_bf16_f32 v28, v34, v36
	s_waitcnt lgkmcnt(4)
	v_cvt_pk_bf16_f32 v29, v38, v40
	s_waitcnt lgkmcnt(2)
	v_cvt_pk_bf16_f32 v30, v42, v44
	s_waitcnt lgkmcnt(0)
	v_cvt_pk_bf16_f32 v31, v46, v48
	v_lshl_add_u64 v[32:33], v[12:13], 0, v[32:33]
	v_mul_u32_u24_e32 v9, 0xb00, v9
	global_store_dwordx4 v[32:33], v[28:31], off nt
	v_lshlrev_b32_e32 v32, 1, v9
	v_mov_b32_e32 v33, v5
	v_cvt_pk_bf16_f32 v28, v35, v37
	v_cvt_pk_bf16_f32 v29, v39, v41
	v_cvt_pk_bf16_f32 v30, v43, v45
	v_cvt_pk_bf16_f32 v31, v47, v49
	v_lshl_add_u64 v[12:13], v[12:13], 0, v[32:33]
	global_store_dwordx4 v[12:13], v[28:31], off nt
	s_waitcnt lgkmcnt(0)

.LBB0_290:
	s_waitcnt vmcnt(0)
	v_mul_f32_e32 v12, v12, v64
	v_mul_f32_e32 v13, v13, v63
	ds_write2_b32 v21, v12, v13 offset0:8 offset1:74
	v_mul_f32_e32 v9, v9, v66
	v_mul_f32_e32 v12, v30, v65
	ds_write2_b32 v21, v9, v12 offset0:140 offset1:206
	v_mul_f32_e32 v9, v39, v68
	v_mul_f32_e32 v12, v40, v67
	ds_write2_b32 v22, v9, v12 offset0:16 offset1:82
	v_mul_f32_e32 v9, v36, v70
	v_mul_f32_e32 v12, v37, v69
	ds_write2_b32 v22, v9, v12 offset0:148 offset1:214
	v_mul_f32_e32 v9, v34, v72
	v_mul_f32_e32 v12, v35, v71
	ds_write2_b32 v23, v9, v12 offset0:24 offset1:90
	v_mul_f32_e32 v9, v33, v74
	v_mul_f32_e32 v12, v38, v73
	ds_write2_b32 v23, v9, v12 offset0:156 offset1:222
	v_mul_f32_e32 v9, v47, v76
	v_mul_f32_e32 v12, v48, v75
	ds_write2_b32 v24, v9, v12 offset0:32 offset1:98
	v_mul_f32_e32 v9, v44, v78
	v_mul_f32_e32 v12, v45, v77
	ds_write2_b32 v24, v9, v12 offset0:164 offset1:230
	v_mul_f32_e32 v9, v42, v80
	v_mul_f32_e32 v12, v43, v79
	ds_write2_b32 v25, v9, v12 offset0:40 offset1:106
	v_mul_f32_e32 v9, v41, v82
	v_mul_f32_e32 v12, v46, v81
	ds_write2_b32 v25, v9, v12 offset0:172 offset1:238
	v_mul_f32_e32 v9, v55, v84
	v_mul_f32_e32 v12, v57, v83
	ds_write2_b32 v26, v9, v12 offset0:48 offset1:114
	v_mul_f32_e32 v9, v53, v86
	v_mul_f32_e32 v12, v54, v85
	ds_write2_b32 v26, v9, v12 offset0:180 offset1:246
	v_mul_f32_e32 v9, v50, v88
	v_mul_f32_e32 v12, v51, v87
	v_mul_f32_e32 v31, v31, v59
	v_mul_f32_e32 v32, v32, v58
	v_mul_f32_e32 v28, v28, v62
	v_mul_f32_e32 v29, v29, v61
	ds_write2_b32 v27, v9, v12 offset0:56 offset1:122
	v_mul_f32_e32 v9, v49, v90
	v_mul_f32_e32 v12, v52, v89
	ds_write2_b32 v14, v31, v32 offset1:66
	ds_write2_b32 v14, v28, v29 offset0:132 offset1:198
	ds_write2_b32 v27, v9, v12 offset0:188 offset1:254
	s_lshl_b32 s6, s56, 5
	s_lshl_b32 s7, s56, 6
	s_waitcnt lgkmcnt(0)
	s_and_b32 s6, s6, 0x60
	s_and_b32 s7, s7, 0x1f00
	s_and_b32 s2, 0xffff, s2
	ds_read2_b32 v[32:33], v16 offset0:33 offset1:41
	ds_read2_b32 v[34:35], v16 offset1:8
	ds_read2_b32 v[36:37], v16 offset0:66 offset1:74
	ds_read2_b32 v[38:39], v16 offset0:99 offset1:107
	ds_read2_b32 v[40:41], v16 offset0:132 offset1:140
	ds_read2_b32 v[42:43], v16 offset0:165 offset1:173
	ds_read2_b32 v[44:45], v16 offset0:198 offset1:206
	ds_read2_b32 v[46:47], v16 offset0:231 offset1:239
	s_or_b32 s6, s6, s7
	s_lshl_b32 s46, s2, 1
	s_bitset1_b32 s6, 7
	v_lshl_add_u64 v[12:13], v[10:11], 0, s[46:47]
	v_mov_b32_e32 v9, v5
	v_lshl_add_u64 v[12:13], v[12:13], 0, v[8:9]
	v_or_b32_e32 v9, s6, v15
	v_lshlrev_b32_e32 v48, 11, v9
	v_mov_b32_e32 v49, v5
	s_waitcnt lgkmcnt(6)
	v_cvt_pk_bf16_f32 v28, v34, v32
	s_waitcnt lgkmcnt(4)
	v_cvt_pk_bf16_f32 v29, v36, v38
	s_waitcnt lgkmcnt(2)
	v_cvt_pk_bf16_f32 v30, v40, v42
	s_waitcnt lgkmcnt(0)
	v_cvt_pk_bf16_f32 v31, v44, v46
	v_lshl_add_u64 v[48:49], v[12:13], 0, v[48:49]
	global_store_dwordx4 v[48:49], v[28:31], off nt
	v_or_b32_e32 v9, s6, v17
	v_lshlrev_b32_e32 v32, 11, v9
	v_cvt_pk_bf16_f32 v28, v35, v33
	v_cvt_pk_bf16_f32 v29, v37, v39
	v_cvt_pk_bf16_f32 v30, v41, v43
	v_cvt_pk_bf16_f32 v31, v45, v47
	ds_read2_b32 v[34:35], v16 offset0:49 offset1:57
	ds_read2_b32 v[36:37], v16 offset0:16 offset1:24
	ds_read2_b32 v[38:39], v16 offset0:82 offset1:90
	ds_read2_b32 v[40:41], v16 offset0:115 offset1:123
	ds_read2_b32 v[42:43], v16 offset0:148 offset1:156
	ds_read2_b32 v[44:45], v16 offset0:181 offset1:189
	ds_read2_b32 v[46:47], v16 offset0:214 offset1:222
	ds_read2_b32 v[48:49], v16 offset0:247 offset1:255
	v_mov_b32_e32 v33, v5
	v_lshl_add_u64 v[32:33], v[12:13], 0, v[32:33]
	v_or_b32_e32 v9, s6, v18
	global_store_dwordx4 v[32:33], v[28:31], off nt
	v_lshlrev_b32_e32 v32, 11, v9
	v_mov_b32_e32 v33, v5
	s_waitcnt lgkmcnt(6)
	v_cvt_pk_bf16_f32 v28, v36, v34
	s_waitcnt lgkmcnt(4)
	v_cvt_pk_bf16_f32 v29, v38, v40
	s_waitcnt lgkmcnt(2)
	v_cvt_pk_bf16_f32 v30, v42, v44
	s_waitcnt lgkmcnt(0)
	v_cvt_pk_bf16_f32 v31, v46, v48
	v_lshl_add_u64 v[32:33], v[12:13], 0, v[32:33]
	v_or_b32_e32 v9, s6, v19
	global_store_dwordx4 v[32:33], v[28:31], off nt
	v_lshlrev_b32_e32 v32, 11, v9
	v_mov_b32_e32 v33, v5
	v_cvt_pk_bf16_f32 v28, v37, v35
	v_cvt_pk_bf16_f32 v29, v39, v41
	v_cvt_pk_bf16_f32 v30, v43, v45
	v_cvt_pk_bf16_f32 v31, v47, v49
	v_lshl_add_u64 v[12:13], v[12:13], 0, v[32:33]
	global_store_dwordx4 v[12:13], v[28:31], off nt
	s_waitcnt lgkmcnt(0)
